# v35 + residual-GEMM epilogue: f32 X stores made write-through (sc0 sc1) so the grid barrier release fence has less dirty L2 to write back
# baseline (speedup 1.0000x reference)
.LBB0_402:
	s_and_b64 vcc, exec, s[6:7]
	s_cbranch_vccz .LBB0_205
	s_ashr_i32 s43, s42, 31
	s_lshl_b64 s[0:1], s[42:43], 2
	s_waitcnt lgkmcnt(0)
	s_add_u32 s0, s62, s0
	s_addc_u32 s1, s63, s1
	v_lshlrev_b32_e32 v0, 4, v179
	v_lshl_add_u64 v[182:183], s[0:1], 0, v[0:1]
	v_xor_b32_e32 v0, 16, v242
	v_cmp_lt_i32_e32 vcc, v0, v252
	v_lshl_or_b32 v180, v179, 2, s42
	v_or_b32_e32 v192, 16, v178
	v_cndmask_b32_e32 v0, v242, v0, vcc
	v_cmp_lt_i32_e32 vcc, v246, v252
	v_lshlrev_b32_e32 v196, 2, v0
	v_ashrrev_i32_e32 v193, 31, v192
	v_cndmask_b32_e32 v0, v242, v246, vcc
	v_cmp_eq_u32_e32 vcc, 0, v179
	v_ashrrev_i32_e32 v179, 31, v178
	v_lshlrev_b64 v[130:131], 12, v[178:179]
	v_or_b32_e32 v188, 32, v178
	v_lshl_add_u64 v[214:215], v[182:183], 0, v[130:131]
	v_lshlrev_b64 v[130:131], 12, v[192:193]
	v_ashrrev_i32_e32 v189, 31, v188
	v_or_b32_e32 v184, 48, v178
	v_lshl_add_u64 v[194:195], v[182:183], 0, v[130:131]
	v_lshlrev_b64 v[130:131], 12, v[188:189]
	v_ashrrev_i32_e32 v185, 31, v184
	v_lshl_add_u64 v[190:191], v[182:183], 0, v[130:131]
	v_lshlrev_b64 v[130:131], 12, v[184:185]
	v_lshl_add_u64 v[186:187], v[182:183], 0, v[130:131]
	global_load_dwordx4 v[198:201], v[214:215], off
	global_load_dwordx4 v[202:205], v[214:215], off offset:64
	global_load_dwordx4 v[206:209], v[214:215], off offset:128
	global_load_dwordx4 v[210:213], v[214:215], off offset:192
	global_load_dwordx4 v[174:177], v[194:195], off
	global_load_dwordx4 v[170:173], v[194:195], off offset:64
	global_load_dwordx4 v[166:169], v[194:195], off offset:128
	global_load_dwordx4 v[162:165], v[194:195], off offset:192
	global_load_dwordx4 v[158:161], v[190:191], off
	global_load_dwordx4 v[154:157], v[190:191], off offset:64
	global_load_dwordx4 v[150:153], v[190:191], off offset:128
	global_load_dwordx4 v[146:149], v[190:191], off offset:192
	global_load_dwordx4 v[142:145], v[186:187], off
	global_load_dwordx4 v[138:141], v[186:187], off offset:64
	global_load_dwordx4 v[134:137], v[186:187], off offset:128
	global_load_dwordx4 v[130:133], v[186:187], off offset:192
	s_lshl_b32 s0, s80, 2
	s_ashr_i32 s1, s0, 31
	s_lshl_b64 s[0:1], s[0:1], 2
	s_add_u32 s0, s66, s0
	s_addc_u32 s1, s67, s1
	s_lshl_b32 s2, s2, 2
	s_add_u32 s6, s0, s2
	v_mov_b32_e32 v181, s43
	v_lshlrev_b32_e32 v0, 2, v0
	s_addc_u32 s7, s1, 0
	v_lshlrev_b64 v[216:217], 10, v[178:179]
	s_waitcnt vmcnt(15)
	v_pk_add_f32 v[128:129], v[128:129], v[200:201]
	v_pk_add_f32 v[126:127], v[126:127], v[198:199]
	v_lshl_add_u64 v[216:217], v[216:217], 0, v[180:181]
	v_mul_f32_e32 v197, v127, v127
	v_mul_f32_e32 v198, v129, v129
	global_store_dwordx4 v[214:215], v[126:129], off sc0 sc1
	v_fmac_f32_e32 v197, v126, v126
	v_fmac_f32_e32 v198, v128, v128
	v_cvt_pk_bf16_f32 v126, v126, v127
	v_cvt_pk_bf16_f32 v127, v128, v129
	v_lshl_add_u64 v[128:129], v[216:217], 1, s[60:61]
	s_waitcnt vmcnt(15)
	v_pk_add_f32 v[122:123], v[122:123], v[202:203]
	global_store_dwordx2 v[128:129], v[126:127], off
	v_pk_add_f32 v[124:125], v[124:125], v[204:205]
	v_mul_f32_e32 v126, v123, v123
	global_store_dwordx4 v[214:215], v[122:125], off offset:64 sc0 sc1
	v_fmac_f32_e32 v126, v122, v122
	s_waitcnt vmcnt(16)
	v_pk_add_f32 v[120:121], v[120:121], v[208:209]
	v_cvt_pk_bf16_f32 v122, v122, v123
	v_cvt_pk_bf16_f32 v123, v124, v125
	v_pk_add_f32 v[118:119], v[118:119], v[206:207]
	global_store_dwordx2 v[128:129], v[122:123], off offset:32
	v_mul_f32_e32 v122, v119, v119
	v_mul_f32_e32 v123, v121, v121
	v_mul_f32_e32 v127, v125, v125
	v_fmac_f32_e32 v122, v118, v118
	v_fmac_f32_e32 v123, v120, v120
	v_add_f32_e32 v197, v197, v198
	v_fmac_f32_e32 v127, v124, v124
	v_add_f32_e32 v122, v122, v123
	v_add_f32_e32 v126, v126, v127
	v_add_f32_e32 v127, v197, v122
	s_waitcnt vmcnt(16)
	v_pk_add_f32 v[124:125], v[116:117], v[212:213]
	v_pk_add_f32 v[122:123], v[114:115], v[210:211]
	v_mul_f32_e32 v115, v125, v125
	v_mul_f32_e32 v114, v123, v123
	v_fmac_f32_e32 v114, v122, v122
	v_fmac_f32_e32 v115, v124, v124
	v_add_f32_e32 v114, v114, v115
	v_add_f32_e32 v114, v126, v114
	v_add_f32_e32 v116, v127, v114
	ds_bpermute_b32 v117, v196, v116
	v_cvt_pk_bf16_f32 v114, v118, v119
	v_cvt_pk_bf16_f32 v115, v120, v121
	global_store_dwordx4 v[214:215], v[118:121], off offset:128 sc0 sc1
	global_store_dwordx2 v[128:129], v[114:115], off offset:64
	s_waitcnt lgkmcnt(0)
	v_add_f32_e32 v114, v116, v117
	ds_bpermute_b32 v115, v0, v114
	v_cvt_pk_bf16_f32 v116, v122, v123
	v_cvt_pk_bf16_f32 v117, v124, v125
	global_store_dwordx4 v[214:215], v[122:125], off offset:192 sc0 sc1
	global_store_dwordx2 v[128:129], v[116:117], off offset:96
	s_and_saveexec_b64 s[14:15], vcc
	s_cbranch_execz .LBB0_405
	v_lshlrev_b64 v[116:117], 6, v[178:179]
	v_lshl_add_u64 v[116:117], s[6:7], 0, v[116:117]
	s_waitcnt lgkmcnt(0)
	v_add_f32_e32 v114, v114, v115
	global_store_dword v[116:117], v114, off
.LBB0_405:
	s_or_b64 exec, exec, s[14:15]
	s_waitcnt lgkmcnt(0)
	v_lshlrev_b64 v[114:115], 10, v[192:193]
	s_waitcnt vmcnt(19)
	v_pk_add_f32 v[112:113], v[112:113], v[176:177]
	v_pk_add_f32 v[110:111], v[110:111], v[174:175]
	v_lshl_add_u64 v[114:115], v[114:115], 0, v[180:181]
	v_mul_f32_e32 v116, v111, v111
	v_mul_f32_e32 v117, v113, v113
	global_store_dwordx4 v[194:195], v[110:113], off sc0 sc1
	v_fmac_f32_e32 v116, v110, v110
	v_fmac_f32_e32 v117, v112, v112
	v_cvt_pk_bf16_f32 v110, v110, v111
	v_cvt_pk_bf16_f32 v111, v112, v113
	v_lshl_add_u64 v[112:113], v[114:115], 1, s[60:61]
	s_waitcnt vmcnt(19)
	v_pk_add_f32 v[106:107], v[106:107], v[170:171]
	global_store_dwordx2 v[112:113], v[110:111], off
	v_pk_add_f32 v[108:109], v[108:109], v[172:173]
	v_mul_f32_e32 v110, v107, v107
	global_store_dwordx4 v[194:195], v[106:109], off offset:64 sc0 sc1
	v_fmac_f32_e32 v110, v106, v106
	s_waitcnt vmcnt(20)
	v_pk_add_f32 v[104:105], v[104:105], v[168:169]
	v_cvt_pk_bf16_f32 v106, v106, v107
	v_cvt_pk_bf16_f32 v107, v108, v109
	v_pk_add_f32 v[102:103], v[102:103], v[166:167]
	global_store_dwordx2 v[112:113], v[106:107], off offset:32
	v_mul_f32_e32 v106, v103, v103
	v_mul_f32_e32 v107, v105, v105
	v_mul_f32_e32 v111, v109, v109
	v_fmac_f32_e32 v106, v102, v102
	v_fmac_f32_e32 v107, v104, v104
	v_add_f32_e32 v116, v116, v117
	v_fmac_f32_e32 v111, v108, v108
	v_add_f32_e32 v106, v106, v107
	v_add_f32_e32 v110, v110, v111
	v_add_f32_e32 v111, v116, v106
	s_waitcnt vmcnt(20)
	v_pk_add_f32 v[108:109], v[100:101], v[164:165]
	v_pk_add_f32 v[106:107], v[98:99], v[162:163]
	v_mul_f32_e32 v99, v109, v109
	v_mul_f32_e32 v98, v107, v107
	v_fmac_f32_e32 v98, v106, v106
	v_fmac_f32_e32 v99, v108, v108
	v_add_f32_e32 v98, v98, v99
	v_add_f32_e32 v98, v110, v98
	v_add_f32_e32 v100, v111, v98
	ds_bpermute_b32 v101, v196, v100
	v_cvt_pk_bf16_f32 v98, v102, v103
	v_cvt_pk_bf16_f32 v99, v104, v105
	global_store_dwordx4 v[194:195], v[102:105], off offset:128 sc0 sc1
	global_store_dwordx2 v[112:113], v[98:99], off offset:64
	s_waitcnt lgkmcnt(0)
	v_add_f32_e32 v98, v100, v101
	ds_bpermute_b32 v99, v0, v98
	v_cvt_pk_bf16_f32 v100, v106, v107
	v_cvt_pk_bf16_f32 v101, v108, v109
	global_store_dwordx4 v[194:195], v[106:109], off offset:192 sc0 sc1
	global_store_dwordx2 v[112:113], v[100:101], off offset:96
	s_and_saveexec_b64 s[14:15], vcc
	s_cbranch_execz .LBB0_407
	v_lshlrev_b64 v[100:101], 6, v[192:193]
	v_lshl_add_u64 v[100:101], s[6:7], 0, v[100:101]
	s_waitcnt lgkmcnt(0)
	v_add_f32_e32 v98, v98, v99
	global_store_dword v[100:101], v98, off
.LBB0_407:
	s_or_b64 exec, exec, s[14:15]
	s_waitcnt lgkmcnt(0)
	v_lshlrev_b64 v[98:99], 10, v[188:189]
	s_waitcnt vmcnt(23)
	v_pk_add_f32 v[96:97], v[96:97], v[160:161]
	v_pk_add_f32 v[94:95], v[94:95], v[158:159]
	v_lshl_add_u64 v[98:99], v[98:99], 0, v[180:181]
	v_mul_f32_e32 v100, v95, v95
	v_mul_f32_e32 v101, v97, v97
	global_store_dwordx4 v[190:191], v[94:97], off sc0 sc1
	v_fmac_f32_e32 v100, v94, v94
	v_fmac_f32_e32 v101, v96, v96
	v_cvt_pk_bf16_f32 v94, v94, v95
	v_cvt_pk_bf16_f32 v95, v96, v97
	v_lshl_add_u64 v[96:97], v[98:99], 1, s[60:61]
	s_waitcnt vmcnt(23)
	v_pk_add_f32 v[90:91], v[90:91], v[154:155]
	global_store_dwordx2 v[96:97], v[94:95], off
	v_pk_add_f32 v[92:93], v[92:93], v[156:157]
	v_mul_f32_e32 v94, v91, v91
	global_store_dwordx4 v[190:191], v[90:93], off offset:64 sc0 sc1
	v_fmac_f32_e32 v94, v90, v90
	s_waitcnt vmcnt(24)
	v_pk_add_f32 v[88:89], v[88:89], v[152:153]
	v_cvt_pk_bf16_f32 v90, v90, v91
	v_cvt_pk_bf16_f32 v91, v92, v93
	v_pk_add_f32 v[86:87], v[86:87], v[150:151]
	global_store_dwordx2 v[96:97], v[90:91], off offset:32
	v_mul_f32_e32 v90, v87, v87
	v_mul_f32_e32 v91, v89, v89
	v_mul_f32_e32 v95, v93, v93
	v_fmac_f32_e32 v90, v86, v86
	v_fmac_f32_e32 v91, v88, v88
	v_add_f32_e32 v100, v100, v101
	v_fmac_f32_e32 v95, v92, v92
	v_add_f32_e32 v90, v90, v91
	v_add_f32_e32 v94, v94, v95
	v_add_f32_e32 v95, v100, v90
	s_waitcnt vmcnt(24)
	v_pk_add_f32 v[92:93], v[84:85], v[148:149]
	v_pk_add_f32 v[90:91], v[82:83], v[146:147]
	v_mul_f32_e32 v83, v93, v93
	v_mul_f32_e32 v82, v91, v91
	v_fmac_f32_e32 v82, v90, v90
	v_fmac_f32_e32 v83, v92, v92
	v_add_f32_e32 v82, v82, v83
	v_add_f32_e32 v82, v94, v82
	v_add_f32_e32 v84, v95, v82
	ds_bpermute_b32 v85, v196, v84
	v_cvt_pk_bf16_f32 v82, v86, v87
	v_cvt_pk_bf16_f32 v83, v88, v89
	global_store_dwordx4 v[190:191], v[86:89], off offset:128 sc0 sc1
	global_store_dwordx2 v[96:97], v[82:83], off offset:64
	s_waitcnt lgkmcnt(0)
	v_add_f32_e32 v82, v84, v85
	ds_bpermute_b32 v83, v0, v82
	v_cvt_pk_bf16_f32 v84, v90, v91
	v_cvt_pk_bf16_f32 v85, v92, v93
	global_store_dwordx4 v[190:191], v[90:93], off offset:192 sc0 sc1
	global_store_dwordx2 v[96:97], v[84:85], off offset:96
	s_and_saveexec_b64 s[14:15], vcc
	s_cbranch_execz .LBB0_409
	v_lshlrev_b64 v[84:85], 6, v[188:189]
	v_lshl_add_u64 v[84:85], s[6:7], 0, v[84:85]
	s_waitcnt lgkmcnt(0)
	v_add_f32_e32 v82, v82, v83
	global_store_dword v[84:85], v82, off
.LBB0_409:
	s_or_b64 exec, exec, s[14:15]
	s_waitcnt lgkmcnt(0)
	v_lshlrev_b64 v[82:83], 10, v[184:185]
	s_waitcnt vmcnt(27)
	v_pk_add_f32 v[80:81], v[80:81], v[144:145]
	v_pk_add_f32 v[78:79], v[78:79], v[142:143]
	v_lshl_add_u64 v[82:83], v[82:83], 0, v[180:181]
	v_mul_f32_e32 v84, v79, v79
	v_mul_f32_e32 v85, v81, v81
	global_store_dwordx4 v[186:187], v[78:81], off sc0 sc1
	v_fmac_f32_e32 v84, v78, v78
	v_fmac_f32_e32 v85, v80, v80
	v_cvt_pk_bf16_f32 v78, v78, v79
	v_cvt_pk_bf16_f32 v79, v80, v81
	v_lshl_add_u64 v[80:81], v[82:83], 1, s[60:61]
	s_waitcnt vmcnt(27)
	v_pk_add_f32 v[74:75], v[74:75], v[138:139]
	global_store_dwordx2 v[80:81], v[78:79], off
	v_pk_add_f32 v[76:77], v[76:77], v[140:141]
	v_mul_f32_e32 v78, v75, v75
	global_store_dwordx4 v[186:187], v[74:77], off offset:64 sc0 sc1
	v_fmac_f32_e32 v78, v74, v74
	s_waitcnt vmcnt(28)
	v_pk_add_f32 v[72:73], v[72:73], v[136:137]
	v_cvt_pk_bf16_f32 v74, v74, v75
	v_cvt_pk_bf16_f32 v75, v76, v77
	v_pk_add_f32 v[70:71], v[70:71], v[134:135]
	global_store_dwordx2 v[80:81], v[74:75], off offset:32
	v_mul_f32_e32 v74, v71, v71
	v_mul_f32_e32 v75, v73, v73
	v_mul_f32_e32 v79, v77, v77
	v_fmac_f32_e32 v74, v70, v70
	v_fmac_f32_e32 v75, v72, v72
	v_add_f32_e32 v84, v84, v85
	v_fmac_f32_e32 v79, v76, v76
	v_add_f32_e32 v74, v74, v75
	v_add_f32_e32 v78, v78, v79
	v_add_f32_e32 v79, v84, v74
	s_waitcnt vmcnt(28)
	v_pk_add_f32 v[76:77], v[68:69], v[132:133]
	v_pk_add_f32 v[74:75], v[66:67], v[130:131]
	v_mul_f32_e32 v67, v77, v77
	v_mul_f32_e32 v66, v75, v75
	v_fmac_f32_e32 v66, v74, v74
	v_fmac_f32_e32 v67, v76, v76
	v_add_f32_e32 v66, v66, v67
	v_add_f32_e32 v66, v78, v66
	v_add_f32_e32 v68, v79, v66
	ds_bpermute_b32 v69, v196, v68
	v_cvt_pk_bf16_f32 v66, v70, v71
	v_cvt_pk_bf16_f32 v67, v72, v73
	global_store_dwordx4 v[186:187], v[70:73], off offset:128 sc0 sc1
	global_store_dwordx2 v[80:81], v[66:67], off offset:64
	s_waitcnt lgkmcnt(0)
	v_add_f32_e32 v66, v68, v69
	ds_bpermute_b32 v67, v0, v66
	v_cvt_pk_bf16_f32 v68, v74, v75
	v_cvt_pk_bf16_f32 v69, v76, v77
	global_store_dwordx4 v[186:187], v[74:77], off offset:192 sc0 sc1
	global_store_dwordx2 v[80:81], v[68:69], off offset:96
	s_and_saveexec_b64 s[14:15], vcc
	s_cbranch_execz .LBB0_411
	v_lshlrev_b64 v[68:69], 6, v[184:185]
	v_lshl_add_u64 v[68:69], s[6:7], 0, v[68:69]
	s_waitcnt lgkmcnt(0)
	v_add_f32_e32 v66, v66, v67
	global_store_dword v[68:69], v66, off
.LBB0_411:
	s_or_b64 exec, exec, s[14:15]
	v_or_b32_e32 v126, 64, v178
	v_ashrrev_i32_e32 v127, 31, v126
	v_or_b32_e32 v122, 0x50, v178
	s_waitcnt lgkmcnt(0)
	v_lshlrev_b64 v[66:67], 12, v[126:127]
	v_ashrrev_i32_e32 v123, 31, v122
	v_or_b32_e32 v118, 0x60, v178
	v_lshl_add_u64 v[144:145], v[182:183], 0, v[66:67]
	v_lshlrev_b64 v[66:67], 12, v[122:123]
	v_ashrrev_i32_e32 v119, 31, v118
	v_or_b32_e32 v114, 0x70, v178
	v_lshl_add_u64 v[124:125], v[182:183], 0, v[66:67]
	v_lshlrev_b64 v[66:67], 12, v[118:119]
	v_ashrrev_i32_e32 v115, 31, v114
	v_lshl_add_u64 v[120:121], v[182:183], 0, v[66:67]
	v_lshlrev_b64 v[66:67], 12, v[114:115]
	v_lshl_add_u64 v[116:117], v[182:183], 0, v[66:67]
	global_load_dwordx4 v[128:131], v[144:145], off
	global_load_dwordx4 v[132:135], v[144:145], off offset:64
	global_load_dwordx4 v[136:139], v[144:145], off offset:128
	global_load_dwordx4 v[140:143], v[144:145], off offset:192
	global_load_dwordx4 v[110:113], v[124:125], off
	global_load_dwordx4 v[106:109], v[124:125], off offset:64
	global_load_dwordx4 v[102:105], v[124:125], off offset:128
	global_load_dwordx4 v[98:101], v[124:125], off offset:192
	global_load_dwordx4 v[94:97], v[120:121], off
	global_load_dwordx4 v[90:93], v[120:121], off offset:64
	global_load_dwordx4 v[86:89], v[120:121], off offset:128
	global_load_dwordx4 v[82:85], v[120:121], off offset:192
	global_load_dwordx4 v[78:81], v[116:117], off
	global_load_dwordx4 v[74:77], v[116:117], off offset:64
	global_load_dwordx4 v[70:73], v[116:117], off offset:128
	global_load_dwordx4 v[66:69], v[116:117], off offset:192
	v_lshlrev_b64 v[146:147], 10, v[126:127]
	s_waitcnt vmcnt(15)
	v_pk_add_f32 v[64:65], v[64:65], v[130:131]
	v_pk_add_f32 v[62:63], v[62:63], v[128:129]
	v_lshl_add_u64 v[146:147], v[146:147], 0, v[180:181]
	v_mul_f32_e32 v128, v63, v63
	v_mul_f32_e32 v129, v65, v65
	global_store_dwordx4 v[144:145], v[62:65], off sc0 sc1
	v_fmac_f32_e32 v128, v62, v62
	v_fmac_f32_e32 v129, v64, v64
	v_cvt_pk_bf16_f32 v62, v62, v63
	v_cvt_pk_bf16_f32 v63, v64, v65
	v_lshl_add_u64 v[64:65], v[146:147], 1, s[60:61]
	s_waitcnt vmcnt(15)
	v_pk_add_f32 v[58:59], v[58:59], v[132:133]
	global_store_dwordx2 v[64:65], v[62:63], off
	v_pk_add_f32 v[60:61], v[60:61], v[134:135]
	v_mul_f32_e32 v62, v59, v59
	global_store_dwordx4 v[144:145], v[58:61], off offset:64 sc0 sc1
	v_fmac_f32_e32 v62, v58, v58
	s_waitcnt vmcnt(16)
	v_pk_add_f32 v[56:57], v[56:57], v[138:139]
	v_cvt_pk_bf16_f32 v58, v58, v59
	v_cvt_pk_bf16_f32 v59, v60, v61
	v_pk_add_f32 v[54:55], v[54:55], v[136:137]
	global_store_dwordx2 v[64:65], v[58:59], off offset:32
	v_mul_f32_e32 v58, v55, v55
	v_mul_f32_e32 v59, v57, v57
	v_mul_f32_e32 v63, v61, v61
	v_fmac_f32_e32 v58, v54, v54
	v_fmac_f32_e32 v59, v56, v56
	v_add_f32_e32 v128, v128, v129
	v_fmac_f32_e32 v63, v60, v60
	v_add_f32_e32 v58, v58, v59
	v_add_f32_e32 v62, v62, v63
	v_add_f32_e32 v63, v128, v58
	s_waitcnt vmcnt(16)
	v_pk_add_f32 v[60:61], v[52:53], v[142:143]
	v_pk_add_f32 v[58:59], v[50:51], v[140:141]
	v_mul_f32_e32 v51, v61, v61
	v_mul_f32_e32 v50, v59, v59
	v_fmac_f32_e32 v50, v58, v58
	v_fmac_f32_e32 v51, v60, v60
	v_add_f32_e32 v50, v50, v51
	v_add_f32_e32 v50, v62, v50
	v_add_f32_e32 v52, v63, v50
	ds_bpermute_b32 v53, v196, v52
	v_cvt_pk_bf16_f32 v50, v54, v55
	v_cvt_pk_bf16_f32 v51, v56, v57
	global_store_dwordx4 v[144:145], v[54:57], off offset:128 sc0 sc1
	global_store_dwordx2 v[64:65], v[50:51], off offset:64
	s_waitcnt lgkmcnt(0)
	v_add_f32_e32 v50, v52, v53
	ds_bpermute_b32 v51, v0, v50
	v_cvt_pk_bf16_f32 v52, v58, v59
	v_cvt_pk_bf16_f32 v53, v60, v61
	global_store_dwordx4 v[144:145], v[58:61], off offset:192 sc0 sc1
	global_store_dwordx2 v[64:65], v[52:53], off offset:96
	s_and_saveexec_b64 s[14:15], vcc
	s_cbranch_execz .LBB0_413
	v_lshlrev_b64 v[52:53], 6, v[126:127]
	v_lshl_add_u64 v[52:53], s[6:7], 0, v[52:53]
	s_waitcnt lgkmcnt(0)
	v_add_f32_e32 v50, v50, v51
	global_store_dword v[52:53], v50, off
.LBB0_413:
	s_or_b64 exec, exec, s[14:15]
	s_waitcnt lgkmcnt(0)
	v_lshlrev_b64 v[50:51], 10, v[122:123]
	s_waitcnt vmcnt(19)
	v_pk_add_f32 v[48:49], v[48:49], v[112:113]
	v_pk_add_f32 v[46:47], v[46:47], v[110:111]
	v_lshl_add_u64 v[50:51], v[50:51], 0, v[180:181]
	v_mul_f32_e32 v52, v47, v47
	v_mul_f32_e32 v53, v49, v49
	global_store_dwordx4 v[124:125], v[46:49], off sc0 sc1
	v_fmac_f32_e32 v52, v46, v46
	v_fmac_f32_e32 v53, v48, v48
	v_cvt_pk_bf16_f32 v46, v46, v47
	v_cvt_pk_bf16_f32 v47, v48, v49
	v_lshl_add_u64 v[48:49], v[50:51], 1, s[60:61]
	s_waitcnt vmcnt(19)
	v_pk_add_f32 v[42:43], v[42:43], v[106:107]
	global_store_dwordx2 v[48:49], v[46:47], off
	v_pk_add_f32 v[44:45], v[44:45], v[108:109]
	v_mul_f32_e32 v46, v43, v43
	global_store_dwordx4 v[124:125], v[42:45], off offset:64 sc0 sc1
	v_fmac_f32_e32 v46, v42, v42
	s_waitcnt vmcnt(20)
	v_pk_add_f32 v[40:41], v[40:41], v[104:105]
	v_cvt_pk_bf16_f32 v42, v42, v43
	v_cvt_pk_bf16_f32 v43, v44, v45
	v_pk_add_f32 v[38:39], v[38:39], v[102:103]
	global_store_dwordx2 v[48:49], v[42:43], off offset:32
	v_mul_f32_e32 v42, v39, v39
	v_mul_f32_e32 v43, v41, v41
	v_mul_f32_e32 v47, v45, v45
	v_fmac_f32_e32 v42, v38, v38
	v_fmac_f32_e32 v43, v40, v40
	v_add_f32_e32 v52, v52, v53
	v_fmac_f32_e32 v47, v44, v44
	v_add_f32_e32 v42, v42, v43
	v_add_f32_e32 v46, v46, v47
	v_add_f32_e32 v47, v52, v42
	s_waitcnt vmcnt(20)
	v_pk_add_f32 v[44:45], v[36:37], v[100:101]
	v_pk_add_f32 v[42:43], v[34:35], v[98:99]
	v_mul_f32_e32 v35, v45, v45
	v_mul_f32_e32 v34, v43, v43
	v_fmac_f32_e32 v34, v42, v42
	v_fmac_f32_e32 v35, v44, v44
	v_add_f32_e32 v34, v34, v35
	v_add_f32_e32 v34, v46, v34
	v_add_f32_e32 v36, v47, v34
	ds_bpermute_b32 v37, v196, v36
	v_cvt_pk_bf16_f32 v34, v38, v39
	v_cvt_pk_bf16_f32 v35, v40, v41
	global_store_dwordx4 v[124:125], v[38:41], off offset:128 sc0 sc1
	global_store_dwordx2 v[48:49], v[34:35], off offset:64
	s_waitcnt lgkmcnt(0)
	v_add_f32_e32 v34, v36, v37
	ds_bpermute_b32 v35, v0, v34
	v_cvt_pk_bf16_f32 v36, v42, v43
	v_cvt_pk_bf16_f32 v37, v44, v45
	global_store_dwordx4 v[124:125], v[42:45], off offset:192 sc0 sc1
	global_store_dwordx2 v[48:49], v[36:37], off offset:96
	s_and_saveexec_b64 s[14:15], vcc
	s_cbranch_execz .LBB0_415
	v_lshlrev_b64 v[36:37], 6, v[122:123]
	v_lshl_add_u64 v[36:37], s[6:7], 0, v[36:37]
	s_waitcnt lgkmcnt(0)
	v_add_f32_e32 v34, v34, v35
	global_store_dword v[36:37], v34, off
.LBB0_415:
	s_or_b64 exec, exec, s[14:15]
	s_waitcnt lgkmcnt(0)
	v_lshlrev_b64 v[34:35], 10, v[118:119]
	s_waitcnt vmcnt(23)
	v_pk_add_f32 v[32:33], v[32:33], v[96:97]
	v_pk_add_f32 v[30:31], v[30:31], v[94:95]
	v_lshl_add_u64 v[34:35], v[34:35], 0, v[180:181]
	v_mul_f32_e32 v36, v31, v31
	v_mul_f32_e32 v37, v33, v33
	global_store_dwordx4 v[120:121], v[30:33], off sc0 sc1
	v_fmac_f32_e32 v36, v30, v30
	v_fmac_f32_e32 v37, v32, v32
	v_cvt_pk_bf16_f32 v30, v30, v31
	v_cvt_pk_bf16_f32 v31, v32, v33
	v_lshl_add_u64 v[32:33], v[34:35], 1, s[60:61]
	s_waitcnt vmcnt(23)
	v_pk_add_f32 v[26:27], v[26:27], v[90:91]
	global_store_dwordx2 v[32:33], v[30:31], off
	v_pk_add_f32 v[28:29], v[28:29], v[92:93]
	v_mul_f32_e32 v30, v27, v27
	global_store_dwordx4 v[120:121], v[26:29], off offset:64 sc0 sc1
	v_fmac_f32_e32 v30, v26, v26
	s_waitcnt vmcnt(24)
	v_pk_add_f32 v[24:25], v[24:25], v[88:89]
	v_cvt_pk_bf16_f32 v26, v26, v27
	v_cvt_pk_bf16_f32 v27, v28, v29
	v_pk_add_f32 v[22:23], v[22:23], v[86:87]
	global_store_dwordx2 v[32:33], v[26:27], off offset:32
	v_mul_f32_e32 v26, v23, v23
	v_mul_f32_e32 v27, v25, v25
	v_mul_f32_e32 v31, v29, v29
	v_fmac_f32_e32 v26, v22, v22
	v_fmac_f32_e32 v27, v24, v24
	v_add_f32_e32 v36, v36, v37
	v_fmac_f32_e32 v31, v28, v28
	v_add_f32_e32 v26, v26, v27
	v_add_f32_e32 v30, v30, v31
	v_add_f32_e32 v31, v36, v26
	s_waitcnt vmcnt(24)
	v_pk_add_f32 v[28:29], v[20:21], v[84:85]
	v_pk_add_f32 v[26:27], v[18:19], v[82:83]
	v_mul_f32_e32 v19, v29, v29
	v_mul_f32_e32 v18, v27, v27
	v_fmac_f32_e32 v18, v26, v26
	v_fmac_f32_e32 v19, v28, v28
	v_add_f32_e32 v18, v18, v19
	v_add_f32_e32 v18, v30, v18
	v_add_f32_e32 v20, v31, v18
	ds_bpermute_b32 v21, v196, v20
	v_cvt_pk_bf16_f32 v18, v22, v23
	v_cvt_pk_bf16_f32 v19, v24, v25
	global_store_dwordx4 v[120:121], v[22:25], off offset:128 sc0 sc1
	global_store_dwordx2 v[32:33], v[18:19], off offset:64
	s_waitcnt lgkmcnt(0)
	v_add_f32_e32 v18, v20, v21
	ds_bpermute_b32 v19, v0, v18
	v_cvt_pk_bf16_f32 v20, v26, v27
	v_cvt_pk_bf16_f32 v21, v28, v29
	global_store_dwordx4 v[120:121], v[26:29], off offset:192 sc0 sc1
	global_store_dwordx2 v[32:33], v[20:21], off offset:96
	s_and_saveexec_b64 s[14:15], vcc
	s_cbranch_execz .LBB0_417
	v_lshlrev_b64 v[20:21], 6, v[118:119]
	v_lshl_add_u64 v[20:21], s[6:7], 0, v[20:21]
	s_waitcnt lgkmcnt(0)
	v_add_f32_e32 v18, v18, v19
	global_store_dword v[20:21], v18, off
.LBB0_417:
	s_or_b64 exec, exec, s[14:15]
	s_waitcnt lgkmcnt(0)
	v_lshlrev_b64 v[18:19], 10, v[114:115]
	s_waitcnt vmcnt(27)
	v_pk_add_f32 v[16:17], v[16:17], v[80:81]
	v_pk_add_f32 v[14:15], v[14:15], v[78:79]
	v_lshl_add_u64 v[18:19], v[18:19], 0, v[180:181]
	v_mul_f32_e32 v20, v15, v15
	v_mul_f32_e32 v21, v17, v17
	global_store_dwordx4 v[116:117], v[14:17], off sc0 sc1
	v_fmac_f32_e32 v20, v14, v14
	v_fmac_f32_e32 v21, v16, v16
	v_cvt_pk_bf16_f32 v14, v14, v15
	v_cvt_pk_bf16_f32 v15, v16, v17
	v_lshl_add_u64 v[16:17], v[18:19], 1, s[60:61]
	s_waitcnt vmcnt(27)
	v_pk_add_f32 v[10:11], v[10:11], v[74:75]
	global_store_dwordx2 v[16:17], v[14:15], off
	v_pk_add_f32 v[12:13], v[12:13], v[76:77]
	v_mul_f32_e32 v14, v11, v11
	global_store_dwordx4 v[116:117], v[10:13], off offset:64 sc0 sc1
	v_fmac_f32_e32 v14, v10, v10
	s_waitcnt vmcnt(28)
	v_pk_add_f32 v[8:9], v[8:9], v[72:73]
	v_cvt_pk_bf16_f32 v10, v10, v11
	v_cvt_pk_bf16_f32 v11, v12, v13
	v_pk_add_f32 v[6:7], v[6:7], v[70:71]
	global_store_dwordx2 v[16:17], v[10:11], off offset:32
	v_mul_f32_e32 v10, v7, v7
	v_mul_f32_e32 v11, v9, v9
	v_mul_f32_e32 v15, v13, v13
	v_fmac_f32_e32 v10, v6, v6
	v_fmac_f32_e32 v11, v8, v8
	v_add_f32_e32 v20, v20, v21
	v_fmac_f32_e32 v15, v12, v12
	v_add_f32_e32 v10, v10, v11
	v_add_f32_e32 v14, v14, v15
	v_add_f32_e32 v15, v20, v10
	s_waitcnt vmcnt(28)
	v_pk_add_f32 v[12:13], v[4:5], v[68:69]
	v_pk_add_f32 v[10:11], v[2:3], v[66:67]
	v_mul_f32_e32 v3, v13, v13
	v_mul_f32_e32 v2, v11, v11
	v_fmac_f32_e32 v2, v10, v10
	v_fmac_f32_e32 v3, v12, v12
	v_add_f32_e32 v2, v2, v3
	v_add_f32_e32 v2, v14, v2
	v_add_f32_e32 v4, v15, v2
	ds_bpermute_b32 v5, v196, v4
	v_cvt_pk_bf16_f32 v2, v6, v7
	v_cvt_pk_bf16_f32 v3, v8, v9
	global_store_dwordx4 v[116:117], v[6:9], off offset:128 sc0 sc1
	global_store_dwordx2 v[16:17], v[2:3], off offset:64
	s_waitcnt lgkmcnt(0)
	v_add_f32_e32 v2, v4, v5
	ds_bpermute_b32 v0, v0, v2
	v_cvt_pk_bf16_f32 v4, v10, v11
	v_cvt_pk_bf16_f32 v5, v12, v13
	global_store_dwordx4 v[116:117], v[10:13], off offset:192 sc0 sc1
	global_store_dwordx2 v[16:17], v[4:5], off offset:96
	s_and_saveexec_b64 s[14:15], vcc
	s_cbranch_execz .LBB0_204
	v_lshlrev_b64 v[4:5], 6, v[114:115]
	v_lshl_add_u64 v[4:5], s[6:7], 0, v[4:5]
	s_waitcnt lgkmcnt(0)
	v_add_f32_e32 v0, v2, v0
	global_store_dword v[4:5], v0, off
	s_branch .LBB0_204
